# v15 + 8 bytes of never-executed padding before the token-mixing code (code placement only)
# speedup vs baseline: 1.0018x; 1.0018x over previous
.LBB0_309:
	s_andn2_b64 vcc, exec, s[84:85]
	s_cbranch_vccnz .LBB0_280
	s_barrier
	s_branch .LBB0_280
	s_nop 0
	s_nop 0
